# FFN up/gate epilogue: delete 154 dead zero-initialising v_mov before full-lane DPP row rotates (4 s_nop re-added for store-data WAR distance)
# speedup vs baseline: 1.0059x; 1.0059x over previous
; __device__ __forceinline__ u32x4 pack8(f32x4 a, f32x4 b) { u32x4 w; w.x = cvtpk(a[0], a[1]); w.y = cvtpk(a[2], a[3]); w.z = cvtpk(b[0], b[1]); w.w = cvtpk(b[2], b[3]); return w; }
; #define FOR_AI_M _Pragma("unroll") for (int ai = 0; ai < 2; ++ai) _Pragma("unroll") for (int m = 0; m < 4; ++m)
; #define FOR_BJ _Pragma("unroll") for (int bj = 0; bj < 2; ++bj)
; __device__ __forceinline__ float dpp_ror1(float v) { return __builtin_bit_cast(float, __builtin_amdgcn_update_dpp(0, __builtin_bit_cast(int, v), 0x121, 0xf, 0xf, false)); }
; __device__ __forceinline__ float dpp_ror2(float v) { return __builtin_bit_cast(float, __builtin_amdgcn_update_dpp(0, __builtin_bit_cast(int, v), 0x122, 0xf, 0xf, false)); }
; __device__ __forceinline__ float silu_mul(float cv, float g) { return cv * __builtin_amdgcn_rcpf(1.f + __builtin_amdgcn_exp2f(-cv * LOG2E)) * g; }
;     __device__ __forceinline__ void operator()(f32x4 (&acc)[2][2][4][2], const Unit& u, int wr, int wc, int fr, int fq) const {
;     ...
;         FOR_AI_M { const int grow = u.pm * BM + ai * HALF + wr * 64 + m * 16 + fr;
;             const f32x4 a0 = *(const f32x4*)(SS3 + (size_t)grow * 8), a1 = *(const f32x4*)(SS3 + (size_t)grow * 8 + 4);
;             const float r3 = rsqrtf(((a0[0] + a0[1]) + (a0[2] + a0[3]) + (a1[0] + a1[1]) + (a1[2] + a1[3])) * (1.f / 2048.f) + EPS);
;             FOR_BJ { acc[ai][bj][m][0] *= r3; acc[ai][bj][m][1] *= r3; } }
;     ...
;             for (int m = 0; m < 4; ++m) {
;                 const int grow = u.pm * BM + ai * HALF + wr * 64 + m * 16 + fr;
;                 f32x4 av[2];
; #pragma unroll
;                 for (int n = 0; n < 2; ++n)
; #pragma unroll
;                     for (int e = 0; e < 4; ++e) {
;                         const float cur = acc[ai][0][m][n][e], prv = pv[n][e];
;                         const float a1 = dpp_ror1(cur), b1 = dpp_ror1(prv), a2 = dpp_ror2(cur), b2 = dpp_ror2(prv);
;                         const float p1 = fr >= 1 ? a1 : b1, p2 = fr >= 2 ? a2 : b2;
;                         const float cv = w0[n][e] * p2 + w1[n][e] * p1 + w2[n][e] * cur;
;                         av[n][e] = silu_mul(cv, acc[ai][1][m][n][e]);
;                     }
;                 *(u32x4*)(ACT + (size_t)grow * DFF + f0) = pack8(av[0], av[1]);
.LBB0_1187:
	v_mul_f32_e32 v188, 0x4b800000, v226
	v_cndmask_b32_e64 v188, v226, v188, s[0:1]
	v_rsq_f32_e32 v188, v188
	v_mov_b32_e32 v225, v224
	v_mov_b32_e32 v205, 0
	s_and_b64 vcc, exec, s[10:11]
	v_mul_f32_e32 v203, 0x45800000, v188
	v_cndmask_b32_e64 v188, v188, v203, s[0:1]
	v_pk_mul_f32 v[228:229], v[148:149], v[188:189] op_sel_hi:[1,0]
	v_pk_mul_f32 v[148:149], v[142:143], v[188:189] op_sel_hi:[1,0]
	v_pk_mul_f32 v[142:143], v[136:137], v[188:189] op_sel_hi:[1,0]
	v_mul_f32_e32 v136, 0x4b800000, v215
	v_cndmask_b32_e64 v136, v215, v136, s[12:13]
	v_rsq_f32_e32 v136, v136
	v_pk_mul_f32 v[150:151], v[150:151], v[188:189] op_sel_hi:[1,0]
	v_pk_mul_f32 v[146:147], v[146:147], v[188:189] op_sel_hi:[1,0]
	v_pk_mul_f32 v[144:145], v[144:145], v[188:189] op_sel_hi:[1,0]
	v_mul_f32_e32 v137, 0x45800000, v136
	v_pk_mul_f32 v[226:227], v[140:141], v[188:189] op_sel_hi:[1,0]
	v_pk_mul_f32 v[140:141], v[138:139], v[188:189] op_sel_hi:[1,0]
	v_cndmask_b32_e64 v188, v136, v137, s[12:13]
	v_pk_mul_f32 v[136:137], v[124:125], v[188:189] op_sel_hi:[1,0]
	v_mov_b32_e32 v124, v224
	v_mov_b32_e32 v125, v224
	v_pk_mul_f32 v[138:139], v[132:133], v[188:189] op_sel_hi:[1,0]
	v_pk_mul_f32 v[132:133], v[126:127], v[188:189] op_sel_hi:[1,0]
	v_pk_mul_f32 v[126:127], v[120:121], v[188:189] op_sel_hi:[1,0]
	v_pk_mul_f32 v[118:119], v[118:119], v[124:125]
	v_pk_mul_f32 v[120:121], v[116:117], v[224:225]
	v_pk_mul_f32 v[114:115], v[114:115], v[124:125]
	v_pk_mul_f32 v[116:117], v[112:113], v[224:225]
	v_pk_mul_f32 v[134:135], v[134:135], v[188:189] op_sel_hi:[1,0]
	v_pk_mul_f32 v[130:131], v[130:131], v[188:189] op_sel_hi:[1,0]
	v_pk_mul_f32 v[128:129], v[128:129], v[188:189] op_sel_hi:[1,0]
	v_pk_mul_f32 v[122:123], v[122:123], v[188:189] op_sel_hi:[1,0]
	s_waitcnt vmcnt(1) lgkmcnt(1)
	v_mov_b32_dpp v112, v172 row_ror:1 row_mask:0xf bank_mask:0xf
	v_mov_b32_dpp v203, v164 row_ror:2 row_mask:0xf bank_mask:0xf
	v_mov_b32_dpp v124, v172 row_ror:2 row_mask:0xf bank_mask:0xf
	v_mov_b32_dpp v205, v165 row_ror:2 row_mask:0xf bank_mask:0xf
	v_mov_b32_dpp v125, v173 row_ror:2 row_mask:0xf bank_mask:0xf
	v_mov_b32_dpp v188, v164 row_ror:1 row_mask:0xf bank_mask:0xf
	v_mov_b32_dpp v172, v165 row_ror:1 row_mask:0xf bank_mask:0xf
	v_mov_b32_dpp v113, v173 row_ror:1 row_mask:0xf bank_mask:0xf
	v_cndmask_b32_e64 v125, v125, v205, s[6:7]
	v_cndmask_b32_e64 v124, v124, v203, s[6:7]
	v_cndmask_b32_e64 v113, v172, v113, s[4:5]
	v_cndmask_b32_e64 v112, v188, v112, s[4:5]
	v_pk_mul_f32 v[124:125], v[100:101], v[124:125]
	v_pk_fma_f32 v[112:113], v[104:105], v[112:113], v[124:125]
	s_waitcnt vmcnt(0)
	v_pk_fma_f32 v[112:113], v[164:165], v[108:109], v[112:113]
	v_mul_f32_e32 v124, 0xbfb8aa3b, v112
	v_mul_f32_e32 v125, 0xbfb8aa3b, v113
	v_exp_f32_e32 v124, v124
	v_exp_f32_e32 v125, v125
	v_mov_b32_dpp v165, v166 row_ror:2 row_mask:0xf bank_mask:0xf
	v_add_f32_e32 v124, 1.0, v124
	v_add_f32_e32 v125, 1.0, v125
	v_rcp_f32_e32 v124, v124
	v_rcp_f32_e32 v125, v125
	v_mov_b32_dpp v164, v166 row_ror:1 row_mask:0xf bank_mask:0xf
	v_mov_b32_dpp v173, v167 row_ror:1 row_mask:0xf bank_mask:0xf
	v_pk_mul_f32 v[112:113], v[112:113], v[124:125]
	s_nop 0
	v_pk_mul_f32 v[112:113], v[160:161], v[112:113]
	v_mov_b32_dpp v124, v174 row_ror:1 row_mask:0xf bank_mask:0xf
	v_mov_b32_dpp v160, v174 row_ror:2 row_mask:0xf bank_mask:0xf
	v_mov_b32_dpp v161, v175 row_ror:2 row_mask:0xf bank_mask:0xf
	v_mov_b32_dpp v174, v167 row_ror:2 row_mask:0xf bank_mask:0xf
	v_mov_b32_dpp v125, v175 row_ror:1 row_mask:0xf bank_mask:0xf
	v_cndmask_b32_e64 v161, v161, v174, s[6:7]
	v_cndmask_b32_e64 v160, v160, v165, s[6:7]
	v_cndmask_b32_e64 v125, v173, v125, s[4:5]
	v_cndmask_b32_e64 v124, v164, v124, s[4:5]
	v_pk_mul_f32 v[160:161], v[102:103], v[160:161]
	v_pk_fma_f32 v[124:125], v[106:107], v[124:125], v[160:161]
	s_nop 0
	v_pk_fma_f32 v[124:125], v[166:167], v[110:111], v[124:125]
	v_mul_f32_e32 v160, 0xbfb8aa3b, v124
	v_mul_f32_e32 v161, 0xbfb8aa3b, v125
	v_exp_f32_e32 v160, v160
	v_exp_f32_e32 v161, v161
	v_mov_b32_dpp v167, v156 row_ror:2 row_mask:0xf bank_mask:0xf
	v_add_f32_e32 v160, 1.0, v160
	v_add_f32_e32 v161, 1.0, v161
	v_rcp_f32_e32 v160, v160
	v_rcp_f32_e32 v161, v161
	v_mov_b32_dpp v175, v157 row_ror:2 row_mask:0xf bank_mask:0xf
	v_mov_b32_dpp v166, v156 row_ror:1 row_mask:0xf bank_mask:0xf
	v_pk_mul_f32 v[124:125], v[124:125], v[160:161]
	s_nop 0
	v_pk_mul_f32 v[124:125], v[162:163], v[124:125]
	s_waitcnt lgkmcnt(0)
; __device__ __forceinline__ u32x4 pack8(f32x4 a, f32x4 b) { u32x4 w; w.x = cvtpk(a[0], a[1]); w.y = cvtpk(a[2], a[3]); w.z = cvtpk(b[0], b[1]); w.w = cvtpk(b[2], b[3]); return w; }
; __device__ __forceinline__ float dpp_ror1(float v) { return __builtin_bit_cast(float, __builtin_amdgcn_update_dpp(0, __builtin_bit_cast(int, v), 0x121, 0xf, 0xf, false)); }
; __device__ __forceinline__ float dpp_ror2(float v) { return __builtin_bit_cast(float, __builtin_amdgcn_update_dpp(0, __builtin_bit_cast(int, v), 0x122, 0xf, 0xf, false)); }
; __device__ __forceinline__ float silu_mul(float cv, float g) { return cv * __builtin_amdgcn_rcpf(1.f + __builtin_amdgcn_exp2f(-cv * LOG2E)) * g; }
;     __device__ __forceinline__ void operator()(f32x4 (&acc)[2][2][4][2], const Unit& u, int wr, int wc, int fr, int fq) const {
;     ...
;             for (int m = 0; m < 4; ++m) {
;                 const int grow = u.pm * BM + ai * HALF + wr * 64 + m * 16 + fr;
;                 f32x4 av[2];
; #pragma unroll
;                 for (int n = 0; n < 2; ++n)
; #pragma unroll
;                     for (int e = 0; e < 4; ++e) {
;                         const float cur = acc[ai][0][m][n][e], prv = pv[n][e];
;                         const float a1 = dpp_ror1(cur), b1 = dpp_ror1(prv), a2 = dpp_ror2(cur), b2 = dpp_ror2(prv);
;                         const float p1 = fr >= 1 ? a1 : b1, p2 = fr >= 2 ? a2 : b2;
;                         const float cv = w0[n][e] * p2 + w1[n][e] * p1 + w2[n][e] * cur;
;                         av[n][e] = silu_mul(cv, acc[ai][1][m][n][e]);
;                     }
;                 *(u32x4*)(ACT + (size_t)grow * DFF + f0) = pack8(av[0], av[1]);
	v_mov_b32_dpp v160, v168 row_ror:1 row_mask:0xf bank_mask:0xf
	v_mov_b32_dpp v162, v168 row_ror:2 row_mask:0xf bank_mask:0xf
	v_mov_b32_dpp v163, v169 row_ror:2 row_mask:0xf bank_mask:0xf
	v_mov_b32_dpp v168, v157 row_ror:1 row_mask:0xf bank_mask:0xf
	v_mov_b32_dpp v161, v169 row_ror:1 row_mask:0xf bank_mask:0xf
	v_cndmask_b32_e64 v163, v163, v175, s[6:7]
	v_cndmask_b32_e64 v162, v162, v167, s[6:7]
	v_cndmask_b32_e64 v161, v168, v161, s[4:5]
	v_cndmask_b32_e64 v160, v166, v160, s[4:5]
	v_pk_mul_f32 v[162:163], v[88:89], v[162:163]
	v_pk_fma_f32 v[160:161], v[92:93], v[160:161], v[162:163]
	v_pk_fma_f32 v[156:157], v[156:157], v[96:97], v[160:161]
	v_mul_f32_e32 v160, 0xbfb8aa3b, v156
	v_mul_f32_e32 v161, 0xbfb8aa3b, v157
	v_exp_f32_e32 v160, v160
	v_exp_f32_e32 v161, v161
	v_mov_b32_dpp v163, v158 row_ror:2 row_mask:0xf bank_mask:0xf
	v_mov_b32_dpp v162, v158 row_ror:1 row_mask:0xf bank_mask:0xf
	v_add_f32_e32 v160, 1.0, v160
	v_add_f32_e32 v161, 1.0, v161
	v_rcp_f32_e32 v160, v160
	v_rcp_f32_e32 v161, v161
	v_mov_b32_dpp v169, v159 row_ror:1 row_mask:0xf bank_mask:0xf
	v_pk_mul_f32 v[156:157], v[156:157], v[160:161]
	s_nop 0
	v_pk_mul_f32 v[156:157], v[152:153], v[156:157]
	v_mov_b32_dpp v152, v170 row_ror:1 row_mask:0xf bank_mask:0xf
	v_mov_b32_dpp v160, v170 row_ror:2 row_mask:0xf bank_mask:0xf
	v_mov_b32_dpp v161, v171 row_ror:2 row_mask:0xf bank_mask:0xf
	v_mov_b32_dpp v170, v159 row_ror:2 row_mask:0xf bank_mask:0xf
	v_mov_b32_dpp v153, v171 row_ror:1 row_mask:0xf bank_mask:0xf
	v_cndmask_b32_e64 v161, v161, v170, s[6:7]
	v_cndmask_b32_e64 v160, v160, v163, s[6:7]
	v_cndmask_b32_e64 v153, v169, v153, s[4:5]
	v_cndmask_b32_e64 v152, v162, v152, s[4:5]
	v_pk_mul_f32 v[160:161], v[90:91], v[160:161]
	v_pk_fma_f32 v[152:153], v[94:95], v[152:153], v[160:161]
	v_pk_fma_f32 v[152:153], v[158:159], v[98:99], v[152:153]
	v_mul_f32_e32 v158, 0xbfb8aa3b, v152
	v_mul_f32_e32 v159, 0xbfb8aa3b, v153
	v_exp_f32_e32 v158, v158
	v_exp_f32_e32 v159, v159
	v_mov_b32_dpp v161, v229 row_ror:2 row_mask:0xf bank_mask:0xf
	v_mov_b32_dpp v160, v229 row_ror:1 row_mask:0xf bank_mask:0xf
	v_add_f32_e32 v158, 1.0, v158
	v_add_f32_e32 v159, 1.0, v159
	v_rcp_f32_e32 v158, v158
	v_rcp_f32_e32 v159, v159
	v_mov_b32_dpp v171, v150 row_ror:1 row_mask:0xf bank_mask:0xf
	v_pk_mul_f32 v[152:153], v[152:153], v[158:159]
	s_nop 0
	v_pk_mul_f32 v[158:159], v[154:155], v[152:153]
	v_cvt_pk_bf16_f32 v153, v124, v125
	v_mov_b64_e32 v[124:125], s[14:15]
	v_cvt_pk_bf16_f32 v152, v112, v113
	v_cvt_pk_bf16_f32 v154, v156, v157
	v_cvt_pk_bf16_f32 v155, v158, v159
	v_mad_i64_i32 v[156:157], s[0:1], v220, s94, v[124:125]
	v_lshlrev_b64 v[112:113], 1, v[222:223]
	v_lshl_add_u64 v[156:157], v[156:157], 0, v[112:113]
	v_mov_b32_dpp v159, v228 row_ror:2 row_mask:0xf bank_mask:0xf
	global_store_dwordx4 v[156:157], v[152:155], off
	v_mov_b32_dpp v158, v228 row_ror:1 row_mask:0xf bank_mask:0xf
	s_nop 0
	v_cndmask_b32_e64 v155, v205, v161, s[6:7]
	v_cndmask_b32_e64 v154, v203, v159, s[6:7]
	v_cndmask_b32_e64 v153, v160, v172, s[4:5]
	v_cndmask_b32_e64 v152, v158, v188, s[4:5]
	v_pk_mul_f32 v[154:155], v[100:101], v[154:155]
	v_pk_fma_f32 v[152:153], v[104:105], v[152:153], v[154:155]
	v_pk_fma_f32 v[152:153], v[228:229], v[108:109], v[152:153]
	v_mov_b32_dpp v172, v150 row_ror:2 row_mask:0xf bank_mask:0xf
	v_mul_f32_e32 v154, 0xbfb8aa3b, v152
	v_mul_f32_e32 v155, 0xbfb8aa3b, v153
	v_exp_f32_e32 v154, v154
	v_exp_f32_e32 v155, v155
	v_mov_b32_dpp v203, v151 row_ror:2 row_mask:0xf bank_mask:0xf
	v_add_f32_e32 v154, 1.0, v154
	v_add_f32_e32 v155, 1.0, v155
	v_rcp_f32_e32 v154, v154
	v_rcp_f32_e32 v155, v155
	v_mov_b32_dpp v188, v151 row_ror:1 row_mask:0xf bank_mask:0xf
	v_cndmask_b32_e64 v157, v174, v203, s[6:7]
	v_cndmask_b32_e64 v156, v165, v172, s[6:7]
	v_pk_mul_f32 v[152:153], v[152:153], v[154:155]
	v_cndmask_b32_e64 v155, v188, v173, s[4:5]
	v_cndmask_b32_e64 v154, v171, v164, s[4:5]
	v_pk_mul_f32 v[156:157], v[102:103], v[156:157]
	v_pk_fma_f32 v[154:155], v[106:107], v[154:155], v[156:157]
	v_pk_fma_f32 v[150:151], v[150:151], v[110:111], v[154:155]
	v_mul_f32_e32 v154, 0xbfb8aa3b, v150
	v_mul_f32_e32 v155, 0xbfb8aa3b, v151
	v_exp_f32_e32 v154, v154
	v_exp_f32_e32 v155, v155
	v_mov_b32_dpp v157, v144 row_ror:2 row_mask:0xf bank_mask:0xf
	v_add_f32_e32 v154, 1.0, v154
	v_add_f32_e32 v155, 1.0, v155
	v_rcp_f32_e32 v154, v154
	v_rcp_f32_e32 v155, v155
	v_mov_b32_dpp v165, v145 row_ror:2 row_mask:0xf bank_mask:0xf
	v_mov_b32_dpp v156, v144 row_ror:1 row_mask:0xf bank_mask:0xf
	v_mov_b32_dpp v164, v145 row_ror:1 row_mask:0xf bank_mask:0xf
	v_pk_mul_f32 v[150:151], v[150:151], v[154:155]
	v_cndmask_b32_e64 v155, v175, v165, s[6:7]
	v_cndmask_b32_e64 v154, v167, v157, s[6:7]
	v_pk_mul_f32 v[148:149], v[148:149], v[150:151]
	v_cndmask_b32_e64 v151, v164, v168, s[4:5]
	v_cndmask_b32_e64 v150, v156, v166, s[4:5]
	v_pk_mul_f32 v[154:155], v[88:89], v[154:155]
	v_pk_fma_f32 v[150:151], v[92:93], v[150:151], v[154:155]
	v_pk_fma_f32 v[144:145], v[144:145], v[96:97], v[150:151]
	v_mul_f32_e32 v150, 0xbfb8aa3b, v144
	v_mul_f32_e32 v151, 0xbfb8aa3b, v145
	v_exp_f32_e32 v150, v150
	v_exp_f32_e32 v151, v151
	v_mov_b32_dpp v155, v146 row_ror:2 row_mask:0xf bank_mask:0xf
	v_add_f32_e32 v150, 1.0, v150
	v_add_f32_e32 v151, 1.0, v151
	v_rcp_f32_e32 v150, v150
	v_rcp_f32_e32 v151, v151
	v_mov_b32_dpp v167, v147 row_ror:2 row_mask:0xf bank_mask:0xf
	v_mov_b32_dpp v154, v146 row_ror:1 row_mask:0xf bank_mask:0xf
	v_mov_b32_dpp v166, v147 row_ror:1 row_mask:0xf bank_mask:0xf
	v_pk_mul_f32 v[144:145], v[144:145], v[150:151]
	v_cndmask_b32_e64 v151, v170, v167, s[6:7]
	v_cndmask_b32_e64 v150, v163, v155, s[6:7]
; __device__ __forceinline__ u32x4 pack8(f32x4 a, f32x4 b) { u32x4 w; w.x = cvtpk(a[0], a[1]); w.y = cvtpk(a[2], a[3]); w.z = cvtpk(b[0], b[1]); w.w = cvtpk(b[2], b[3]); return w; }
; __device__ __forceinline__ float dpp_ror1(float v) { return __builtin_bit_cast(float, __builtin_amdgcn_update_dpp(0, __builtin_bit_cast(int, v), 0x121, 0xf, 0xf, false)); }
; __device__ __forceinline__ float dpp_ror2(float v) { return __builtin_bit_cast(float, __builtin_amdgcn_update_dpp(0, __builtin_bit_cast(int, v), 0x122, 0xf, 0xf, false)); }
; __device__ __forceinline__ float silu_mul(float cv, float g) { return cv * __builtin_amdgcn_rcpf(1.f + __builtin_amdgcn_exp2f(-cv * LOG2E)) * g; }
;     __device__ __forceinline__ void operator()(f32x4 (&acc)[2][2][4][2], const Unit& u, int wr, int wc, int fr, int fq) const {
;     ...
;             for (int m = 0; m < 4; ++m) {
;                 const int grow = u.pm * BM + ai * HALF + wr * 64 + m * 16 + fr;
;                 f32x4 av[2];
; #pragma unroll
;                 for (int n = 0; n < 2; ++n)
; #pragma unroll
;                     for (int e = 0; e < 4; ++e) {
;                         const float cur = acc[ai][0][m][n][e], prv = pv[n][e];
;                         const float a1 = dpp_ror1(cur), b1 = dpp_ror1(prv), a2 = dpp_ror2(cur), b2 = dpp_ror2(prv);
;                         const float p1 = fr >= 1 ? a1 : b1, p2 = fr >= 2 ? a2 : b2;
;                         const float cv = w0[n][e] * p2 + w1[n][e] * p1 + w2[n][e] * cur;
;                         av[n][e] = silu_mul(cv, acc[ai][1][m][n][e]);
;                     }
;                 *(u32x4*)(ACT + (size_t)grow * DFF + f0) = pack8(av[0], av[1]);
	v_pk_mul_f32 v[142:143], v[142:143], v[144:145]
	v_cndmask_b32_e64 v145, v166, v169, s[4:5]
	v_cndmask_b32_e64 v144, v154, v162, s[4:5]
	v_pk_mul_f32 v[150:151], v[90:91], v[150:151]
	v_pk_mul_f32 v[152:153], v[226:227], v[152:153]
	v_pk_fma_f32 v[144:145], v[94:95], v[144:145], v[150:151]
	v_cvt_pk_bf16_f32 v142, v142, v143
	v_pk_fma_f32 v[144:145], v[146:147], v[98:99], v[144:145]
	v_mul_f32_e32 v146, 0xbfb8aa3b, v144
	v_mul_f32_e32 v147, 0xbfb8aa3b, v145
	v_exp_f32_e32 v146, v146
	v_exp_f32_e32 v147, v147
	v_mov_b32_dpp v151, v129 row_ror:2 row_mask:0xf bank_mask:0xf
	v_add_f32_e32 v146, 1.0, v146
	v_add_f32_e32 v147, 1.0, v147
	v_rcp_f32_e32 v146, v146
	v_rcp_f32_e32 v147, v147
	v_mov_b32_dpp v150, v129 row_ror:1 row_mask:0xf bank_mask:0xf
	v_pk_mul_f32 v[144:145], v[144:145], v[146:147]
	s_nop 0
	v_pk_mul_f32 v[144:145], v[140:141], v[144:145]
	v_cvt_pk_bf16_f32 v140, v152, v153
	v_cvt_pk_bf16_f32 v143, v144, v145
	v_mad_i64_i32 v[144:145], s[0:1], v216, s94, v[124:125]
	v_cvt_pk_bf16_f32 v141, v148, v149
	v_lshl_add_u64 v[144:145], v[144:145], 0, v[112:113]
	global_store_dwordx4 v[144:145], v[140:143], off
	v_mov_b32_dpp v145, v138 row_ror:2 row_mask:0xf bank_mask:0xf
	v_mov_b32_dpp v147, v139 row_ror:2 row_mask:0xf bank_mask:0xf
	v_mov_b32_dpp v144, v138 row_ror:1 row_mask:0xf bank_mask:0xf
	v_mov_b32_dpp v146, v139 row_ror:1 row_mask:0xf bank_mask:0xf
	v_cndmask_b32_e64 v143, v161, v147, s[6:7]
	v_cndmask_b32_e64 v142, v159, v145, s[6:7]
	v_cndmask_b32_e64 v141, v146, v160, s[4:5]
	v_cndmask_b32_e64 v140, v144, v158, s[4:5]
	v_pk_mul_f32 v[142:143], v[100:101], v[142:143]
	v_pk_fma_f32 v[140:141], v[104:105], v[140:141], v[142:143]
	v_pk_fma_f32 v[138:139], v[138:139], v[108:109], v[140:141]
	v_mul_f32_e32 v140, 0xbfb8aa3b, v138
	v_mul_f32_e32 v141, 0xbfb8aa3b, v139
	v_exp_f32_e32 v140, v140
	v_exp_f32_e32 v141, v141
	v_mov_b32_dpp v143, v134 row_ror:2 row_mask:0xf bank_mask:0xf
	v_add_f32_e32 v140, 1.0, v140
	v_add_f32_e32 v141, 1.0, v141
	v_rcp_f32_e32 v140, v140
	v_rcp_f32_e32 v141, v141
	v_mov_b32_dpp v149, v135 row_ror:2 row_mask:0xf bank_mask:0xf
	v_mov_b32_dpp v142, v134 row_ror:1 row_mask:0xf bank_mask:0xf
	v_mov_b32_dpp v148, v135 row_ror:1 row_mask:0xf bank_mask:0xf
	v_pk_mul_f32 v[138:139], v[138:139], v[140:141]
	v_cndmask_b32_e64 v141, v203, v149, s[6:7]
	v_cndmask_b32_e64 v140, v172, v143, s[6:7]
	v_pk_mul_f32 v[136:137], v[136:137], v[138:139]
	v_cndmask_b32_e64 v139, v148, v188, s[4:5]
	v_cndmask_b32_e64 v138, v142, v171, s[4:5]
	v_pk_mul_f32 v[140:141], v[102:103], v[140:141]
	v_pk_fma_f32 v[138:139], v[106:107], v[138:139], v[140:141]
	v_pk_fma_f32 v[134:135], v[134:135], v[110:111], v[138:139]
	v_mul_f32_e32 v138, 0xbfb8aa3b, v134
	v_mul_f32_e32 v139, 0xbfb8aa3b, v135
	v_exp_f32_e32 v138, v138
	v_exp_f32_e32 v139, v139
	v_mov_b32_dpp v141, v128 row_ror:2 row_mask:0xf bank_mask:0xf
	v_mov_b32_dpp v140, v128 row_ror:1 row_mask:0xf bank_mask:0xf
	v_add_f32_e32 v138, 1.0, v138
	v_add_f32_e32 v139, 1.0, v139
	v_rcp_f32_e32 v138, v138
	v_rcp_f32_e32 v139, v139
	v_mov_b32_dpp v153, v131 row_ror:2 row_mask:0xf bank_mask:0xf
	v_pk_mul_f32 v[134:135], v[134:135], v[138:139]
	v_cndmask_b32_e64 v139, v165, v151, s[6:7]
	v_cndmask_b32_e64 v138, v157, v141, s[6:7]
	v_pk_mul_f32 v[132:133], v[132:133], v[134:135]
	v_cndmask_b32_e64 v135, v150, v164, s[4:5]
	v_cndmask_b32_e64 v134, v140, v156, s[4:5]
	v_pk_mul_f32 v[138:139], v[88:89], v[138:139]
	v_mov_b32_dpp v152, v131 row_ror:1 row_mask:0xf bank_mask:0xf
	v_pk_fma_f32 v[134:135], v[92:93], v[134:135], v[138:139]
	v_pk_fma_f32 v[128:129], v[128:129], v[96:97], v[134:135]
	v_mul_f32_e32 v134, 0xbfb8aa3b, v128
	v_mul_f32_e32 v135, 0xbfb8aa3b, v129
	v_exp_f32_e32 v134, v134
	v_exp_f32_e32 v135, v135
	v_mov_b32_dpp v139, v130 row_ror:2 row_mask:0xf bank_mask:0xf
	v_mov_b32_dpp v138, v130 row_ror:1 row_mask:0xf bank_mask:0xf
	v_add_f32_e32 v134, 1.0, v134
	v_add_f32_e32 v135, 1.0, v135
	v_rcp_f32_e32 v134, v134
	v_rcp_f32_e32 v135, v135
	s_nop 0
	v_pk_mul_f32 v[128:129], v[128:129], v[134:135]
	v_cndmask_b32_e64 v135, v167, v153, s[6:7]
	v_cndmask_b32_e64 v134, v155, v139, s[6:7]
	v_pk_mul_f32 v[128:129], v[126:127], v[128:129]
	v_cndmask_b32_e64 v127, v152, v166, s[4:5]
	v_cndmask_b32_e64 v126, v138, v154, s[4:5]
	v_pk_mul_f32 v[134:135], v[90:91], v[134:135]
	v_cvt_pk_bf16_f32 v128, v128, v129
	v_pk_fma_f32 v[126:127], v[94:95], v[126:127], v[134:135]
	s_nop 0
	v_pk_fma_f32 v[126:127], v[130:131], v[98:99], v[126:127]
	s_nop 0
	v_mul_f32_e32 v130, 0xbfb8aa3b, v126
	v_mul_f32_e32 v131, 0xbfb8aa3b, v127
	v_exp_f32_e32 v130, v130
	v_exp_f32_e32 v131, v131
	v_add_f32_e32 v130, 1.0, v130
	v_add_f32_e32 v131, 1.0, v131
; __device__ __forceinline__ u32x4 pack8(f32x4 a, f32x4 b) { u32x4 w; w.x = cvtpk(a[0], a[1]); w.y = cvtpk(a[2], a[3]); w.z = cvtpk(b[0], b[1]); w.w = cvtpk(b[2], b[3]); return w; }
; __device__ __forceinline__ float dpp_ror1(float v) { return __builtin_bit_cast(float, __builtin_amdgcn_update_dpp(0, __builtin_bit_cast(int, v), 0x121, 0xf, 0xf, false)); }
; __device__ __forceinline__ float dpp_ror2(float v) { return __builtin_bit_cast(float, __builtin_amdgcn_update_dpp(0, __builtin_bit_cast(int, v), 0x122, 0xf, 0xf, false)); }
; __device__ __forceinline__ float silu_mul(float cv, float g) { return cv * __builtin_amdgcn_rcpf(1.f + __builtin_amdgcn_exp2f(-cv * LOG2E)) * g; }
;     __device__ __forceinline__ void operator()(f32x4 (&acc)[2][2][4][2], const Unit& u, int wr, int wc, int fr, int fq) const {
;     ...
;             for (int m = 0; m < 4; ++m) {
;                 const int grow = u.pm * BM + ai * HALF + wr * 64 + m * 16 + fr;
;                 f32x4 av[2];
; #pragma unroll
;                 for (int n = 0; n < 2; ++n)
; #pragma unroll
;                     for (int e = 0; e < 4; ++e) {
;                         const float cur = acc[ai][0][m][n][e], prv = pv[n][e];
;                         const float a1 = dpp_ror1(cur), b1 = dpp_ror1(prv), a2 = dpp_ror2(cur), b2 = dpp_ror2(prv);
;                         const float p1 = fr >= 1 ? a1 : b1, p2 = fr >= 2 ? a2 : b2;
;                         const float cv = w0[n][e] * p2 + w1[n][e] * p1 + w2[n][e] * cur;
;                         av[n][e] = silu_mul(cv, acc[ai][1][m][n][e]);
;                     }
;                 *(u32x4*)(ACT + (size_t)grow * DFF + f0) = pack8(av[0], av[1]);
;                 pv[0] = acc[ai][0][m][0]; pv[1] = acc[ai][0][m][1];
;             }
	v_rcp_f32_e32 v130, v130
	v_rcp_f32_e32 v131, v131
	s_nop 0
	v_pk_mul_f32 v[126:127], v[126:127], v[130:131]
	s_nop 0
	v_pk_mul_f32 v[122:123], v[122:123], v[126:127]
	v_cvt_pk_bf16_f32 v126, v136, v137
	v_cvt_pk_bf16_f32 v129, v122, v123
	v_mad_i64_i32 v[122:123], s[0:1], v212, s94, v[124:125]
	v_cvt_pk_bf16_f32 v127, v132, v133
	v_lshl_add_u64 v[122:123], v[122:123], 0, v[112:113]
	global_store_dwordx4 v[122:123], v[126:129], off
	v_mov_b32_dpp v122, v84 row_ror:1 row_mask:0xf bank_mask:0xf
	s_nop 0
	v_mov_b32_dpp v126, v84 row_ror:2 row_mask:0xf bank_mask:0xf
	v_mov_b32_dpp v127, v85 row_ror:2 row_mask:0xf bank_mask:0xf
	v_mov_b32_dpp v123, v85 row_ror:1 row_mask:0xf bank_mask:0xf
	v_cndmask_b32_e64 v127, v147, v127, s[6:7]
	v_cndmask_b32_e64 v126, v145, v126, s[6:7]
	v_cndmask_b32_e64 v123, v123, v146, s[4:5]
	v_cndmask_b32_e64 v122, v122, v144, s[4:5]
	v_pk_mul_f32 v[126:127], v[100:101], v[126:127]
	s_nop 0
	v_pk_fma_f32 v[122:123], v[104:105], v[122:123], v[126:127]
	s_nop 0
	v_pk_fma_f32 v[84:85], v[84:85], v[108:109], v[122:123]
	s_nop 0
	v_mul_f32_e32 v122, 0xbfb8aa3b, v84
	v_mul_f32_e32 v123, 0xbfb8aa3b, v85
	v_exp_f32_e32 v122, v122
	v_exp_f32_e32 v123, v123
	v_add_f32_e32 v122, 1.0, v122
	v_add_f32_e32 v123, 1.0, v123
	v_rcp_f32_e32 v122, v122
	v_rcp_f32_e32 v123, v123
	s_nop 0
	v_pk_mul_f32 v[84:85], v[84:85], v[122:123]
	v_pk_mul_f32 v[84:85], v[120:121], v[84:85]
	v_mov_b32_dpp v122, v86 row_ror:2 row_mask:0xf bank_mask:0xf
	v_mov_b32_dpp v123, v87 row_ror:2 row_mask:0xf bank_mask:0xf
	v_mov_b32_dpp v120, v86 row_ror:1 row_mask:0xf bank_mask:0xf
	v_mov_b32_dpp v121, v87 row_ror:1 row_mask:0xf bank_mask:0xf
	v_cndmask_b32_e64 v123, v149, v123, s[6:7]
	v_cndmask_b32_e64 v122, v143, v122, s[6:7]
	v_cndmask_b32_e64 v121, v121, v148, s[4:5]
	v_cndmask_b32_e64 v120, v120, v142, s[4:5]
	v_pk_mul_f32 v[122:123], v[102:103], v[122:123]
	s_nop 0
	v_pk_fma_f32 v[120:121], v[106:107], v[120:121], v[122:123]
	s_nop 0
	v_pk_fma_f32 v[86:87], v[86:87], v[110:111], v[120:121]
	s_nop 0
	v_mul_f32_e32 v120, 0xbfb8aa3b, v86
	v_mul_f32_e32 v121, 0xbfb8aa3b, v87
	v_exp_f32_e32 v120, v120
	v_exp_f32_e32 v121, v121
	v_add_f32_e32 v120, 1.0, v120
	v_add_f32_e32 v121, 1.0, v121
	v_rcp_f32_e32 v120, v120
	v_rcp_f32_e32 v121, v121
	s_nop 0
	v_pk_mul_f32 v[86:87], v[86:87], v[120:121]
	v_pk_mul_f32 v[86:87], v[118:119], v[86:87]
	v_mov_b32_dpp v120, v80 row_ror:2 row_mask:0xf bank_mask:0xf
	v_mov_b32_dpp v121, v81 row_ror:2 row_mask:0xf bank_mask:0xf
	v_mov_b32_dpp v118, v80 row_ror:1 row_mask:0xf bank_mask:0xf
	v_mov_b32_dpp v119, v81 row_ror:1 row_mask:0xf bank_mask:0xf
	v_cndmask_b32_e64 v121, v151, v121, s[6:7]
	v_cndmask_b32_e64 v120, v141, v120, s[6:7]
	v_cndmask_b32_e64 v119, v119, v150, s[4:5]
	v_cndmask_b32_e64 v118, v118, v140, s[4:5]
	v_pk_mul_f32 v[120:121], v[88:89], v[120:121]
	s_nop 0
	v_pk_fma_f32 v[118:119], v[92:93], v[118:119], v[120:121]
	s_nop 0
	v_pk_fma_f32 v[80:81], v[80:81], v[96:97], v[118:119]
	s_nop 0
	v_mul_f32_e32 v118, 0xbfb8aa3b, v80
	v_mul_f32_e32 v119, 0xbfb8aa3b, v81
	v_exp_f32_e32 v118, v118
	v_exp_f32_e32 v119, v119
	v_add_f32_e32 v118, 1.0, v118
	v_add_f32_e32 v119, 1.0, v119
	v_rcp_f32_e32 v118, v118
	v_rcp_f32_e32 v119, v119
	s_nop 0
	v_pk_mul_f32 v[80:81], v[80:81], v[118:119]
	v_pk_mul_f32 v[116:117], v[116:117], v[80:81]
	v_mov_b32_dpp v118, v82 row_ror:2 row_mask:0xf bank_mask:0xf
	v_mov_b32_dpp v119, v83 row_ror:2 row_mask:0xf bank_mask:0xf
	v_mov_b32_dpp v80, v82 row_ror:1 row_mask:0xf bank_mask:0xf
	v_mov_b32_dpp v81, v83 row_ror:1 row_mask:0xf bank_mask:0xf
	v_cndmask_b32_e64 v119, v153, v119, s[6:7]
	v_cndmask_b32_e64 v118, v139, v118, s[6:7]
	v_cndmask_b32_e64 v81, v81, v152, s[4:5]
	v_cndmask_b32_e64 v80, v80, v138, s[4:5]
	v_pk_mul_f32 v[118:119], v[90:91], v[118:119]
	s_nop 0
	v_pk_fma_f32 v[80:81], v[94:95], v[80:81], v[118:119]
	s_nop 0
	v_pk_fma_f32 v[80:81], v[82:83], v[98:99], v[80:81]
	s_nop 0
	v_mul_f32_e32 v82, 0xbfb8aa3b, v80
	v_mul_f32_e32 v83, 0xbfb8aa3b, v81
	v_exp_f32_e32 v82, v82
	v_exp_f32_e32 v83, v83
	v_add_f32_e32 v82, 1.0, v82
	v_add_f32_e32 v83, 1.0, v83
	v_rcp_f32_e32 v82, v82
	v_rcp_f32_e32 v83, v83
	s_nop 0
	v_pk_mul_f32 v[80:81], v[80:81], v[82:83]
	s_nop 0
	v_pk_mul_f32 v[114:115], v[114:115], v[80:81]
	v_cvt_pk_bf16_f32 v80, v84, v85
	v_mad_i64_i32 v[84:85], s[0:1], v210, s94, v[124:125]
	v_cvt_pk_bf16_f32 v81, v86, v87
	v_cvt_pk_bf16_f32 v82, v116, v117
	v_cvt_pk_bf16_f32 v83, v114, v115
	v_lshl_add_u64 v[84:85], v[84:85], 0, v[112:113]
	s_mov_b64 s[0:1], -1
	global_store_dwordx4 v[84:85], v[80:83], off
	s_cbranch_vccnz .LBB0_1189
	ds_read_b128 v[84:87], v230
	ds_read_b128 v[80:83], v230 offset:16
	s_mov_b64 s[0:1], 0

; __device__ __forceinline__ u32x4 pack8(f32x4 a, f32x4 b) { u32x4 w; w.x = cvtpk(a[0], a[1]); w.y = cvtpk(a[2], a[3]); w.z = cvtpk(b[0], b[1]); w.w = cvtpk(b[2], b[3]); return w; }
; #define FOR_BJ _Pragma("unroll") for (int bj = 0; bj < 2; ++bj)
; __device__ __forceinline__ float dpp_ror1(float v) { return __builtin_bit_cast(float, __builtin_amdgcn_update_dpp(0, __builtin_bit_cast(int, v), 0x121, 0xf, 0xf, false)); }
; __device__ __forceinline__ float dpp_ror2(float v) { return __builtin_bit_cast(float, __builtin_amdgcn_update_dpp(0, __builtin_bit_cast(int, v), 0x122, 0xf, 0xf, false)); }
; __device__ __forceinline__ float silu_mul(float cv, float g) { return cv * __builtin_amdgcn_rcpf(1.f + __builtin_amdgcn_exp2f(-cv * LOG2E)) * g; }
;     __device__ __forceinline__ void operator()(f32x4 (&acc)[2][2][4][2], const Unit& u, int wr, int wc, int fr, int fq) const {
;     ...
;             const f32x4 a0 = *(const f32x4*)(SS3 + (size_t)grow * 8), a1 = *(const f32x4*)(SS3 + (size_t)grow * 8 + 4);
;             const float r3 = rsqrtf(((a0[0] + a0[1]) + (a0[2] + a0[3]) + (a1[0] + a1[1]) + (a1[2] + a1[3])) * (1.f / 2048.f) + EPS);
;             FOR_BJ { acc[ai][bj][m][0] *= r3; acc[ai][bj][m][1] *= r3; } }
;     ...
;             for (int m = 0; m < 4; ++m) {
;                 const int grow = u.pm * BM + ai * HALF + wr * 64 + m * 16 + fr;
;                 f32x4 av[2];
; #pragma unroll
;                 for (int n = 0; n < 2; ++n)
; #pragma unroll
;                     for (int e = 0; e < 4; ++e) {
;                         const float cur = acc[ai][0][m][n][e], prv = pv[n][e];
;                         const float a1 = dpp_ror1(cur), b1 = dpp_ror1(prv), a2 = dpp_ror2(cur), b2 = dpp_ror2(prv);
;                         const float p1 = fr >= 1 ? a1 : b1, p2 = fr >= 2 ? a2 : b2;
;                         const float cv = w0[n][e] * p2 + w1[n][e] * p1 + w2[n][e] * cur;
;                         av[n][e] = silu_mul(cv, acc[ai][1][m][n][e]);
;                     }
;                 *(u32x4*)(ACT + (size_t)grow * DFF + f0) = pack8(av[0], av[1]);
.LBB0_1191:
	v_mov_b32_e32 v114, v77
	v_mov_b32_e32 v115, v78
	v_mov_b32_e32 v77, v79
	v_mov_b32_e32 v78, v74
	v_mov_b32_e32 v79, v72
	v_mov_b32_e32 v72, v75
	v_mov_b32_e32 v74, v69
	v_mov_b32_e32 v75, v70
	v_mov_b32_e32 v69, v71
	v_pk_add_f32 v[76:77], v[114:115], v[76:77]
	v_pk_add_f32 v[68:69], v[74:75], v[68:69]
	v_mov_b32_e32 v70, v66
	v_mov_b32_e32 v71, v64
	v_mov_b32_e32 v64, v67
	v_pk_add_f32 v[72:73], v[78:79], v[72:73]
	v_pk_add_f32 v[64:65], v[70:71], v[64:65]
	v_mov_b32_e32 v66, v68
	v_mov_b32_e32 v67, v76
	v_mov_b32_e32 v76, v69
	v_pk_add_f32 v[66:67], v[66:67], v[76:77]
	v_mov_b32_e32 v68, v65
	v_mov_b32_e32 v69, v73
	v_pk_add_f32 v[66:67], v[66:67], v[68:69]
	v_mov_b32_e32 v65, v72
	v_pk_add_f32 v[64:65], v[64:65], v[66:67]
	v_pk_fma_f32 v[64:65], v[64:65], s[58:59], v[200:201] op_sel_hi:[1,0,0]
	v_mov_b32_e32 v74, 0
	v_mul_f32_e32 v66, 0x4b800000, v65
	v_cmp_gt_f32_e32 vcc, s85, v65
	v_mov_b32_e32 v77, 0
	v_mov_b32_e32 v79, 0
	v_cndmask_b32_e32 v65, v65, v66, vcc
	v_rsq_f32_e32 v65, v65
	v_mov_b32_e32 v76, 0
	v_mov_b32_e32 v78, 0
	v_mov_b32_e32 v215, v214
	v_mul_f32_e32 v66, 0x45800000, v65
	v_cndmask_b32_e32 v66, v65, v66, vcc
	v_pk_mul_f32 v[68:69], v[38:39], v[66:67] op_sel_hi:[1,0]
	v_mul_f32_e32 v38, 0x4b800000, v64
	v_cmp_gt_f32_e32 vcc, s85, v64
	v_pk_mul_f32 v[54:55], v[54:55], v[66:67] op_sel_hi:[1,0]
	v_pk_mul_f32 v[52:53], v[52:53], v[66:67] op_sel_hi:[1,0]
	v_cndmask_b32_e32 v38, v64, v38, vcc
	v_rsq_f32_e32 v38, v38
	v_pk_mul_f32 v[50:51], v[50:51], v[66:67] op_sel_hi:[1,0]
	v_pk_mul_f32 v[48:49], v[48:49], v[66:67] op_sel_hi:[1,0]
	v_pk_mul_f32 v[64:65], v[36:37], v[66:67] op_sel_hi:[1,0]
	v_pk_mul_f32 v[70:71], v[34:35], v[66:67] op_sel_hi:[1,0]
	v_pk_mul_f32 v[66:67], v[32:33], v[66:67] op_sel_hi:[1,0]
	v_mul_f32_e32 v32, 0x45800000, v38
	v_cndmask_b32_e32 v38, v38, v32, vcc
	v_pk_mul_f32 v[32:33], v[22:23], v[38:39] op_sel_hi:[1,0]
	v_mul_f32_e32 v22, 0x4b800000, v219
	v_cndmask_b32_e64 v22, v219, v22, s[8:9]
	v_rsq_f32_e32 v22, v22
	v_pk_mul_f32 v[46:47], v[46:47], v[38:39] op_sel_hi:[1,0]
	v_pk_mul_f32 v[44:45], v[44:45], v[38:39] op_sel_hi:[1,0]
	v_pk_mul_f32 v[36:37], v[42:43], v[38:39] op_sel_hi:[1,0]
	v_pk_mul_f32 v[40:41], v[40:41], v[38:39] op_sel_hi:[1,0]
	v_pk_mul_f32 v[42:43], v[20:21], v[38:39] op_sel_hi:[1,0]
	v_pk_mul_f32 v[34:35], v[18:19], v[38:39] op_sel_hi:[1,0]
	v_pk_mul_f32 v[38:39], v[16:17], v[38:39] op_sel_hi:[1,0]
	v_mul_f32_e32 v16, 0x45800000, v22
	v_cndmask_b32_e64 v72, v22, v16, s[8:9]
	v_pk_mul_f32 v[20:21], v[30:31], v[72:73] op_sel_hi:[1,0]
	v_pk_mul_f32 v[28:29], v[28:29], v[72:73] op_sel_hi:[1,0]
	v_pk_mul_f32 v[16:17], v[26:27], v[72:73] op_sel_hi:[1,0]
	v_pk_mul_f32 v[18:19], v[24:25], v[72:73] op_sel_hi:[1,0]
	v_pk_mul_f32 v[14:15], v[14:15], v[72:73] op_sel_hi:[1,0]
	v_pk_mul_f32 v[22:23], v[12:13], v[72:73] op_sel_hi:[1,0]
	v_pk_mul_f32 v[10:11], v[10:11], v[72:73] op_sel_hi:[1,0]
	v_pk_mul_f32 v[8:9], v[8:9], v[72:73] op_sel_hi:[1,0]
	v_mov_b32_dpp v73, v52 row_ror:2 row_mask:0xf bank_mask:0xf
	s_waitcnt vmcnt(0) lgkmcnt(1)
	v_mov_b32_dpp v26, v84 row_ror:2 row_mask:0xf bank_mask:0xf
	v_mov_b32_dpp v75, v53 row_ror:2 row_mask:0xf bank_mask:0xf
	v_mov_b32_dpp v27, v85 row_ror:2 row_mask:0xf bank_mask:0xf
	v_mov_b32_dpp v72, v52 row_ror:1 row_mask:0xf bank_mask:0xf
	v_mov_b32_dpp v24, v84 row_ror:1 row_mask:0xf bank_mask:0xf
	v_mov_b32_dpp v74, v53 row_ror:1 row_mask:0xf bank_mask:0xf
	v_mov_b32_dpp v25, v85 row_ror:1 row_mask:0xf bank_mask:0xf
	v_cndmask_b32_e64 v27, v27, v75, s[6:7]
	v_cndmask_b32_e64 v26, v26, v73, s[6:7]
	v_cndmask_b32_e64 v25, v74, v25, s[4:5]
	v_cndmask_b32_e64 v24, v72, v24, s[4:5]
	v_pk_mul_f32 v[26:27], v[100:101], v[26:27]
	v_mov_b32_e32 v12, v214
	v_pk_fma_f32 v[24:25], v[104:105], v[24:25], v[26:27]
	v_mov_b32_e32 v13, v214
	v_pk_fma_f32 v[24:25], v[52:53], v[108:109], v[24:25]
	v_pk_mul_f32 v[6:7], v[6:7], v[12:13]
	v_mul_f32_e32 v26, 0xbfb8aa3b, v24
	v_mul_f32_e32 v27, 0xbfb8aa3b, v25
	v_exp_f32_e32 v26, v26
	v_exp_f32_e32 v27, v27
	v_pk_mul_f32 v[2:3], v[2:3], v[12:13]
	v_mov_b32_dpp v77, v54 row_ror:2 row_mask:0xf bank_mask:0xf
	v_add_f32_e32 v26, 1.0, v26
	v_add_f32_e32 v27, 1.0, v27
	v_rcp_f32_e32 v26, v26
	v_rcp_f32_e32 v27, v27
	v_mov_b32_dpp v79, v55 row_ror:2 row_mask:0xf bank_mask:0xf
	v_mov_b32_dpp v76, v54 row_ror:1 row_mask:0xf bank_mask:0xf
	v_mov_b32_dpp v78, v55 row_ror:1 row_mask:0xf bank_mask:0xf
	v_pk_mul_f32 v[12:13], v[24:25], v[26:27]
	v_mov_b32_dpp v26, v86 row_ror:2 row_mask:0xf bank_mask:0xf
	v_mov_b32_dpp v27, v87 row_ror:2 row_mask:0xf bank_mask:0xf
	v_mov_b32_dpp v24, v86 row_ror:1 row_mask:0xf bank_mask:0xf
	v_mov_b32_dpp v25, v87 row_ror:1 row_mask:0xf bank_mask:0xf
	v_cndmask_b32_e64 v27, v27, v79, s[6:7]
	v_cndmask_b32_e64 v26, v26, v77, s[6:7]
	v_cndmask_b32_e64 v25, v78, v25, s[4:5]
	v_cndmask_b32_e64 v24, v76, v24, s[4:5]
	v_pk_mul_f32 v[26:27], v[102:103], v[26:27]
	v_pk_mul_f32 v[12:13], v[64:65], v[12:13]
	v_pk_fma_f32 v[24:25], v[106:107], v[24:25], v[26:27]
	v_pk_fma_f32 v[24:25], v[54:55], v[110:111], v[24:25]
	v_mul_f32_e32 v26, 0xbfb8aa3b, v24
	v_mul_f32_e32 v27, 0xbfb8aa3b, v25
	v_mov_b32_dpp v55, v48 row_ror:2 row_mask:0xf bank_mask:0xf
	s_waitcnt lgkmcnt(0)
; __device__ __forceinline__ u32x4 pack8(f32x4 a, f32x4 b) { u32x4 w; w.x = cvtpk(a[0], a[1]); w.y = cvtpk(a[2], a[3]); w.z = cvtpk(b[0], b[1]); w.w = cvtpk(b[2], b[3]); return w; }
; __device__ __forceinline__ float dpp_ror1(float v) { return __builtin_bit_cast(float, __builtin_amdgcn_update_dpp(0, __builtin_bit_cast(int, v), 0x121, 0xf, 0xf, false)); }
; __device__ __forceinline__ float dpp_ror2(float v) { return __builtin_bit_cast(float, __builtin_amdgcn_update_dpp(0, __builtin_bit_cast(int, v), 0x122, 0xf, 0xf, false)); }
; __device__ __forceinline__ float silu_mul(float cv, float g) { return cv * __builtin_amdgcn_rcpf(1.f + __builtin_amdgcn_exp2f(-cv * LOG2E)) * g; }
;     __device__ __forceinline__ void operator()(f32x4 (&acc)[2][2][4][2], const Unit& u, int wr, int wc, int fr, int fq) const {
;     ...
;             for (int m = 0; m < 4; ++m) {
;                 const int grow = u.pm * BM + ai * HALF + wr * 64 + m * 16 + fr;
;                 f32x4 av[2];
; #pragma unroll
;                 for (int n = 0; n < 2; ++n)
; #pragma unroll
;                     for (int e = 0; e < 4; ++e) {
;                         const float cur = acc[ai][0][m][n][e], prv = pv[n][e];
;                         const float a1 = dpp_ror1(cur), b1 = dpp_ror1(prv), a2 = dpp_ror2(cur), b2 = dpp_ror2(prv);
;                         const float p1 = fr >= 1 ? a1 : b1, p2 = fr >= 2 ? a2 : b2;
;                         const float cv = w0[n][e] * p2 + w1[n][e] * p1 + w2[n][e] * cur;
;                         av[n][e] = silu_mul(cv, acc[ai][1][m][n][e]);
;                     }
;                 *(u32x4*)(ACT + (size_t)grow * DFF + f0) = pack8(av[0], av[1]);
	v_mov_b32_dpp v52, v80 row_ror:2 row_mask:0xf bank_mask:0xf
	v_mov_b32_dpp v65, v49 row_ror:2 row_mask:0xf bank_mask:0xf
	v_mov_b32_dpp v53, v81 row_ror:2 row_mask:0xf bank_mask:0xf
	v_exp_f32_e32 v26, v26
	v_exp_f32_e32 v27, v27
	v_mov_b32_dpp v54, v48 row_ror:1 row_mask:0xf bank_mask:0xf
	v_mov_b32_dpp v30, v80 row_ror:1 row_mask:0xf bank_mask:0xf
	v_mov_b32_dpp v64, v49 row_ror:1 row_mask:0xf bank_mask:0xf
	v_mov_b32_dpp v31, v81 row_ror:1 row_mask:0xf bank_mask:0xf
	v_cndmask_b32_e64 v53, v53, v65, s[6:7]
	v_cndmask_b32_e64 v52, v52, v55, s[6:7]
	v_cndmask_b32_e64 v31, v64, v31, s[4:5]
	v_cndmask_b32_e64 v30, v54, v30, s[4:5]
	v_pk_mul_f32 v[52:53], v[88:89], v[52:53]
	v_add_f32_e32 v26, 1.0, v26
	v_pk_fma_f32 v[30:31], v[92:93], v[30:31], v[52:53]
	v_add_f32_e32 v27, 1.0, v27
	v_pk_fma_f32 v[30:31], v[48:49], v[96:97], v[30:31]
	v_rcp_f32_e32 v26, v26
	v_mul_f32_e32 v48, 0xbfb8aa3b, v30
	v_rcp_f32_e32 v27, v27
	v_exp_f32_e32 v48, v48
	v_mul_f32_e32 v49, 0xbfb8aa3b, v31
	v_exp_f32_e32 v49, v49
	v_pk_mul_f32 v[24:25], v[24:25], v[26:27]
	v_add_f32_e32 v26, 1.0, v48
	v_add_f32_e32 v27, 1.0, v49
	v_mov_b32_dpp v48, v82 row_ror:1 row_mask:0xf bank_mask:0xf
	v_mov_b32_dpp v81, v50 row_ror:2 row_mask:0xf bank_mask:0xf
	v_mov_b32_dpp v52, v82 row_ror:2 row_mask:0xf bank_mask:0xf
	v_mov_b32_dpp v84, v51 row_ror:2 row_mask:0xf bank_mask:0xf
	v_mov_b32_dpp v53, v83 row_ror:2 row_mask:0xf bank_mask:0xf
	v_mov_b32_dpp v80, v50 row_ror:1 row_mask:0xf bank_mask:0xf
	v_mov_b32_dpp v82, v51 row_ror:1 row_mask:0xf bank_mask:0xf
	v_mov_b32_dpp v49, v83 row_ror:1 row_mask:0xf bank_mask:0xf
	v_cndmask_b32_e64 v53, v53, v84, s[6:7]
	v_cndmask_b32_e64 v52, v52, v81, s[6:7]
	v_cndmask_b32_e64 v49, v82, v49, s[4:5]
	v_cndmask_b32_e64 v48, v80, v48, s[4:5]
	v_pk_mul_f32 v[52:53], v[90:91], v[52:53]
	v_rcp_f32_e32 v26, v26
	v_pk_fma_f32 v[48:49], v[94:95], v[48:49], v[52:53]
	v_rcp_f32_e32 v27, v27
	v_pk_fma_f32 v[48:49], v[50:51], v[98:99], v[48:49]
	v_pk_mul_f32 v[52:53], v[68:69], v[24:25]
	v_mul_f32_e32 v50, 0xbfb8aa3b, v48
	v_mul_f32_e32 v51, 0xbfb8aa3b, v49
	v_exp_f32_e32 v50, v50
	v_exp_f32_e32 v51, v51
	v_pk_mul_f32 v[24:25], v[30:31], v[26:27]
	v_add_f32_e32 v50, 1.0, v50
	v_add_f32_e32 v51, 1.0, v51
	v_rcp_f32_e32 v50, v50
	v_rcp_f32_e32 v51, v51
	v_pk_mul_f32 v[26:27], v[66:67], v[24:25]
	v_cvt_pk_bf16_f32 v26, v26, v27
	v_pk_mul_f32 v[24:25], v[48:49], v[50:51]
	v_pk_mul_f32 v[30:31], v[70:71], v[24:25]
	v_cvt_pk_bf16_f32 v25, v52, v53
	v_mov_b32_dpp v51, v44 row_ror:2 row_mask:0xf bank_mask:0xf
	v_mov_b32_dpp v53, v45 row_ror:2 row_mask:0xf bank_mask:0xf
	v_cvt_pk_bf16_f32 v27, v30, v31
	v_mov_b32_dpp v50, v44 row_ror:1 row_mask:0xf bank_mask:0xf
	v_mov_b32_dpp v52, v45 row_ror:1 row_mask:0xf bank_mask:0xf
	v_cndmask_b32_e64 v31, v75, v53, s[6:7]
	v_cndmask_b32_e64 v30, v73, v51, s[6:7]
	v_cvt_pk_bf16_f32 v24, v12, v13
	v_cndmask_b32_e64 v13, v52, v74, s[4:5]
	v_cndmask_b32_e64 v12, v50, v72, s[4:5]
	v_pk_mul_f32 v[30:31], v[100:101], v[30:31]
	v_pk_fma_f32 v[12:13], v[104:105], v[12:13], v[30:31]
	v_mov_b32_dpp v67, v47 row_ror:2 row_mask:0xf bank_mask:0xf
	v_pk_fma_f32 v[30:31], v[44:45], v[108:109], v[12:13]
	v_mov_b32_dpp v66, v47 row_ror:1 row_mask:0xf bank_mask:0xf
	v_mul_f32_e32 v12, 0xbfb8aa3b, v30
	v_exp_f32_e32 v44, v12
	v_mul_f32_e32 v12, 0xbfb8aa3b, v31
	v_exp_f32_e32 v45, v12
	v_mov_b64_e32 v[12:13], s[14:15]
	v_add_f32_e32 v44, 1.0, v44
	v_rcp_f32_e32 v44, v44
	v_add_f32_e32 v45, 1.0, v45
	v_rcp_f32_e32 v45, v45
	v_mad_i64_i32 v[48:49], s[0:1], v208, s94, v[12:13]
	v_lshl_add_u64 v[48:49], v[48:49], 0, v[112:113]
	global_store_dwordx4 v[48:49], v[24:27], off
	s_nop 1
	v_pk_mul_f32 v[24:25], v[30:31], v[44:45]
	v_mov_b32_dpp v49, v46 row_ror:2 row_mask:0xf bank_mask:0xf
	v_mov_b32_dpp v48, v46 row_ror:1 row_mask:0xf bank_mask:0xf
	v_cndmask_b32_e64 v31, v79, v67, s[6:7]
	v_cndmask_b32_e64 v30, v77, v49, s[6:7]
	v_cndmask_b32_e64 v27, v66, v78, s[4:5]
	v_cndmask_b32_e64 v26, v48, v76, s[4:5]
	v_pk_mul_f32 v[30:31], v[102:103], v[30:31]
	v_pk_fma_f32 v[26:27], v[106:107], v[26:27], v[30:31]
	v_mov_b32_dpp v69, v41 row_ror:2 row_mask:0xf bank_mask:0xf
	v_pk_fma_f32 v[26:27], v[46:47], v[110:111], v[26:27]
	v_mul_f32_e32 v30, 0xbfb8aa3b, v26
	v_mul_f32_e32 v31, 0xbfb8aa3b, v27
	v_mov_b32_dpp v47, v40 row_ror:2 row_mask:0xf bank_mask:0xf
	v_exp_f32_e32 v30, v30
	v_exp_f32_e32 v31, v31
	v_mov_b32_dpp v46, v40 row_ror:1 row_mask:0xf bank_mask:0xf
	v_mov_b32_dpp v68, v41 row_ror:1 row_mask:0xf bank_mask:0xf
	v_cndmask_b32_e64 v45, v65, v69, s[6:7]
	v_cndmask_b32_e64 v44, v55, v47, s[6:7]
	v_pk_mul_f32 v[24:25], v[42:43], v[24:25]
	v_cndmask_b32_e64 v43, v68, v64, s[4:5]
	v_cndmask_b32_e64 v42, v46, v54, s[4:5]
	v_pk_mul_f32 v[44:45], v[88:89], v[44:45]
	v_add_f32_e32 v30, 1.0, v30
	v_pk_fma_f32 v[42:43], v[92:93], v[42:43], v[44:45]
	v_add_f32_e32 v31, 1.0, v31
	v_pk_fma_f32 v[40:41], v[40:41], v[96:97], v[42:43]
	v_rcp_f32_e32 v30, v30
	v_mul_f32_e32 v42, 0xbfb8aa3b, v40
	v_mul_f32_e32 v43, 0xbfb8aa3b, v41
	v_rcp_f32_e32 v31, v31
	v_exp_f32_e32 v42, v42
	v_exp_f32_e32 v43, v43
	v_mov_b32_dpp v55, v36 row_ror:2 row_mask:0xf bank_mask:0xf
	v_mov_b32_dpp v65, v37 row_ror:2 row_mask:0xf bank_mask:0xf
	v_mov_b32_dpp v54, v36 row_ror:1 row_mask:0xf bank_mask:0xf
	v_mov_b32_dpp v64, v37 row_ror:1 row_mask:0xf bank_mask:0xf
	v_cndmask_b32_e64 v45, v84, v65, s[6:7]
	v_cndmask_b32_e64 v44, v81, v55, s[6:7]
	v_pk_mul_f32 v[26:27], v[26:27], v[30:31]
	v_add_f32_e32 v30, 1.0, v42
	v_add_f32_e32 v31, 1.0, v43
	v_cndmask_b32_e64 v43, v64, v82, s[4:5]
	v_cndmask_b32_e64 v42, v54, v80, s[4:5]
	v_pk_mul_f32 v[44:45], v[90:91], v[44:45]
	v_rcp_f32_e32 v30, v30
; __device__ __forceinline__ u32x4 pack8(f32x4 a, f32x4 b) { u32x4 w; w.x = cvtpk(a[0], a[1]); w.y = cvtpk(a[2], a[3]); w.z = cvtpk(b[0], b[1]); w.w = cvtpk(b[2], b[3]); return w; }
; __device__ __forceinline__ float dpp_ror1(float v) { return __builtin_bit_cast(float, __builtin_amdgcn_update_dpp(0, __builtin_bit_cast(int, v), 0x121, 0xf, 0xf, false)); }
; __device__ __forceinline__ float dpp_ror2(float v) { return __builtin_bit_cast(float, __builtin_amdgcn_update_dpp(0, __builtin_bit_cast(int, v), 0x122, 0xf, 0xf, false)); }
; __device__ __forceinline__ float silu_mul(float cv, float g) { return cv * __builtin_amdgcn_rcpf(1.f + __builtin_amdgcn_exp2f(-cv * LOG2E)) * g; }
;     __device__ __forceinline__ void operator()(f32x4 (&acc)[2][2][4][2], const Unit& u, int wr, int wc, int fr, int fq) const {
;     ...
;             for (int m = 0; m < 4; ++m) {
;                 const int grow = u.pm * BM + ai * HALF + wr * 64 + m * 16 + fr;
;                 f32x4 av[2];
; #pragma unroll
;                 for (int n = 0; n < 2; ++n)
; #pragma unroll
;                     for (int e = 0; e < 4; ++e) {
;                         const float cur = acc[ai][0][m][n][e], prv = pv[n][e];
;                         const float a1 = dpp_ror1(cur), b1 = dpp_ror1(prv), a2 = dpp_ror2(cur), b2 = dpp_ror2(prv);
;                         const float p1 = fr >= 1 ? a1 : b1, p2 = fr >= 2 ? a2 : b2;
;                         const float cv = w0[n][e] * p2 + w1[n][e] * p1 + w2[n][e] * cur;
;                         av[n][e] = silu_mul(cv, acc[ai][1][m][n][e]);
;                     }
;                 *(u32x4*)(ACT + (size_t)grow * DFF + f0) = pack8(av[0], av[1]);
	v_pk_fma_f32 v[42:43], v[94:95], v[42:43], v[44:45]
	v_rcp_f32_e32 v31, v31
	v_pk_fma_f32 v[36:37], v[36:37], v[98:99], v[42:43]
	v_pk_mul_f32 v[26:27], v[32:33], v[26:27]
	v_mul_f32_e32 v42, 0xbfb8aa3b, v36
	v_mul_f32_e32 v43, 0xbfb8aa3b, v37
	v_exp_f32_e32 v42, v42
	v_exp_f32_e32 v43, v43
	v_pk_mul_f32 v[30:31], v[40:41], v[30:31]
	v_cvt_pk_bf16_f32 v24, v24, v25
	v_add_f32_e32 v42, 1.0, v42
	v_add_f32_e32 v43, 1.0, v43
	v_rcp_f32_e32 v42, v42
	v_rcp_f32_e32 v43, v43
	v_pk_mul_f32 v[30:31], v[38:39], v[30:31]
	v_pk_mul_f32 v[32:33], v[36:37], v[42:43]
	v_mov_b32_dpp v39, v29 row_ror:2 row_mask:0xf bank_mask:0xf
	v_mov_b32_dpp v37, v28 row_ror:2 row_mask:0xf bank_mask:0xf
	v_pk_mul_f32 v[32:33], v[34:35], v[32:33]
	v_mov_b32_dpp v36, v28 row_ror:1 row_mask:0xf bank_mask:0xf
	v_mov_b32_dpp v38, v29 row_ror:1 row_mask:0xf bank_mask:0xf
	v_cndmask_b32_e64 v35, v53, v39, s[6:7]
	v_cndmask_b32_e64 v34, v51, v37, s[6:7]
	v_cvt_pk_bf16_f32 v25, v26, v27
	v_cvt_pk_bf16_f32 v26, v30, v31
	v_cndmask_b32_e64 v31, v38, v52, s[4:5]
	v_cndmask_b32_e64 v30, v36, v50, s[4:5]
	v_pk_mul_f32 v[34:35], v[100:101], v[34:35]
	v_pk_fma_f32 v[30:31], v[104:105], v[30:31], v[34:35]
	v_pk_fma_f32 v[28:29], v[28:29], v[108:109], v[30:31]
	v_mul_f32_e32 v27, 0xbfb8aa3b, v28
	v_exp_f32_e32 v30, v27
	v_mul_f32_e32 v27, 0xbfb8aa3b, v29
	v_exp_f32_e32 v31, v27
	v_cvt_pk_bf16_f32 v27, v32, v33
	v_add_f32_e32 v30, 1.0, v30
	v_rcp_f32_e32 v30, v30
	v_add_f32_e32 v31, 1.0, v31
	v_rcp_f32_e32 v31, v31
	v_mad_i64_i32 v[32:33], s[0:1], v204, s94, v[12:13]
	v_lshl_add_u64 v[32:33], v[32:33], 0, v[112:113]
	global_store_dwordx4 v[32:33], v[24:27], off
	s_nop 1
	v_pk_mul_f32 v[24:25], v[28:29], v[30:31]
	v_mov_b32_dpp v33, v21 row_ror:2 row_mask:0xf bank_mask:0xf
	v_mov_b32_dpp v31, v20 row_ror:2 row_mask:0xf bank_mask:0xf
	v_mov_b32_dpp v30, v20 row_ror:1 row_mask:0xf bank_mask:0xf
	v_mov_b32_dpp v32, v21 row_ror:1 row_mask:0xf bank_mask:0xf
	v_cndmask_b32_e64 v29, v67, v33, s[6:7]
	v_cndmask_b32_e64 v28, v49, v31, s[6:7]
	v_cndmask_b32_e64 v27, v32, v66, s[4:5]
	v_cndmask_b32_e64 v26, v30, v48, s[4:5]
	v_pk_mul_f32 v[28:29], v[102:103], v[28:29]
	v_mov_b32_dpp v35, v18 row_ror:2 row_mask:0xf bank_mask:0xf
	v_pk_fma_f32 v[26:27], v[106:107], v[26:27], v[28:29]
	v_pk_fma_f32 v[20:21], v[20:21], v[110:111], v[26:27]
	v_mov_b32_dpp v41, v19 row_ror:2 row_mask:0xf bank_mask:0xf
	v_mul_f32_e32 v26, 0xbfb8aa3b, v20
	v_mul_f32_e32 v27, 0xbfb8aa3b, v21
	v_exp_f32_e32 v26, v26
	v_exp_f32_e32 v27, v27
	v_mov_b32_dpp v34, v18 row_ror:1 row_mask:0xf bank_mask:0xf
	v_mov_b32_dpp v40, v19 row_ror:1 row_mask:0xf bank_mask:0xf
	v_cndmask_b32_e64 v29, v69, v41, s[6:7]
	v_cndmask_b32_e64 v28, v47, v35, s[6:7]
	v_pk_mul_f32 v[22:23], v[22:23], v[24:25]
	v_add_f32_e32 v24, 1.0, v26
	v_add_f32_e32 v25, 1.0, v27
	v_cndmask_b32_e64 v27, v40, v68, s[4:5]
	v_cndmask_b32_e64 v26, v34, v46, s[4:5]
	v_pk_mul_f32 v[28:29], v[88:89], v[28:29]
	v_rcp_f32_e32 v24, v24
	v_pk_fma_f32 v[26:27], v[92:93], v[26:27], v[28:29]
	v_rcp_f32_e32 v25, v25
	v_pk_fma_f32 v[18:19], v[18:19], v[96:97], v[26:27]
	v_mul_f32_e32 v26, 0xbfb8aa3b, v18
	v_mul_f32_e32 v27, 0xbfb8aa3b, v19
	v_exp_f32_e32 v26, v26
	v_exp_f32_e32 v27, v27
	v_mov_b32_dpp v43, v16 row_ror:2 row_mask:0xf bank_mask:0xf
	v_mov_b32_dpp v45, v17 row_ror:2 row_mask:0xf bank_mask:0xf
	v_mov_b32_dpp v42, v16 row_ror:1 row_mask:0xf bank_mask:0xf
	v_mov_b32_dpp v44, v17 row_ror:1 row_mask:0xf bank_mask:0xf
	v_cndmask_b32_e64 v29, v65, v45, s[6:7]
	v_cndmask_b32_e64 v28, v55, v43, s[6:7]
	v_pk_mul_f32 v[20:21], v[20:21], v[24:25]
	v_add_f32_e32 v24, 1.0, v26
	v_add_f32_e32 v25, 1.0, v27
	v_cndmask_b32_e64 v27, v44, v64, s[4:5]
	v_cndmask_b32_e64 v26, v42, v54, s[4:5]
	v_pk_mul_f32 v[28:29], v[90:91], v[28:29]
	v_rcp_f32_e32 v24, v24
	v_pk_fma_f32 v[26:27], v[94:95], v[26:27], v[28:29]
	v_rcp_f32_e32 v25, v25
	v_pk_fma_f32 v[16:17], v[16:17], v[98:99], v[26:27]
	v_pk_mul_f32 v[14:15], v[14:15], v[20:21]
	v_mul_f32_e32 v26, 0xbfb8aa3b, v16
	v_mul_f32_e32 v27, 0xbfb8aa3b, v17
	v_exp_f32_e32 v26, v26
	v_exp_f32_e32 v27, v27
	v_pk_mul_f32 v[18:19], v[18:19], v[24:25]
	v_pk_mul_f32 v[4:5], v[4:5], v[214:215]
	v_add_f32_e32 v26, 1.0, v26
	v_add_f32_e32 v27, 1.0, v27
	v_rcp_f32_e32 v26, v26
	v_rcp_f32_e32 v27, v27
	v_pk_mul_f32 v[18:19], v[8:9], v[18:19]
; __device__ __forceinline__ u32x4 pack8(f32x4 a, f32x4 b) { u32x4 w; w.x = cvtpk(a[0], a[1]); w.y = cvtpk(a[2], a[3]); w.z = cvtpk(b[0], b[1]); w.w = cvtpk(b[2], b[3]); return w; }
; #define PG8_BAR __builtin_amdgcn_s_barrier()
; __device__ __forceinline__ float dpp_ror1(float v) { return __builtin_bit_cast(float, __builtin_amdgcn_update_dpp(0, __builtin_bit_cast(int, v), 0x121, 0xf, 0xf, false)); }
; __device__ __forceinline__ float dpp_ror2(float v) { return __builtin_bit_cast(float, __builtin_amdgcn_update_dpp(0, __builtin_bit_cast(int, v), 0x122, 0xf, 0xf, false)); }
; __device__ __forceinline__ float silu_mul(float cv, float g) { return cv * __builtin_amdgcn_rcpf(1.f + __builtin_amdgcn_exp2f(-cv * LOG2E)) * g; }
; template <class Epi>
; __device__ __forceinline__ void gemm_phase(LAS unsigned char* lds, const bf16_t* A0, const bf16_t* B0, const bf16_t* A1, const bf16_t* B1, const int K, const Order& S, const Epi& E) {
;     ...
;         if (wr == 1) PG8_BAR;
;     __device__ __forceinline__ void operator()(f32x4 (&acc)[2][2][4][2], const Unit& u, int wr, int wc, int fr, int fq) const {
;     ...
;             for (int m = 0; m < 4; ++m) {
;                 const int grow = u.pm * BM + ai * HALF + wr * 64 + m * 16 + fr;
;                 f32x4 av[2];
; #pragma unroll
;                 for (int n = 0; n < 2; ++n)
; #pragma unroll
;                     for (int e = 0; e < 4; ++e) {
;                         const float cur = acc[ai][0][m][n][e], prv = pv[n][e];
;                         const float a1 = dpp_ror1(cur), b1 = dpp_ror1(prv), a2 = dpp_ror2(cur), b2 = dpp_ror2(prv);
;                         const float p1 = fr >= 1 ? a1 : b1, p2 = fr >= 2 ? a2 : b2;
;                         const float cv = w0[n][e] * p2 + w1[n][e] * p1 + w2[n][e] * cur;
;                         av[n][e] = silu_mul(cv, acc[ai][1][m][n][e]);
;                     }
;                 *(u32x4*)(ACT + (size_t)grow * DFF + f0) = pack8(av[0], av[1]);
;                 pv[0] = acc[ai][0][m][0]; pv[1] = acc[ai][0][m][1];
;             }
	v_pk_mul_f32 v[0:1], v[0:1], v[214:215]
	s_andn2_b64 vcc, exec, s[68:69]
	v_pk_mul_f32 v[8:9], v[16:17], v[26:27]
	s_nop 0
	v_pk_mul_f32 v[16:17], v[10:11], v[8:9]
	v_cvt_pk_bf16_f32 v10, v18, v19
	v_cvt_pk_bf16_f32 v9, v14, v15
	v_mov_b32_dpp v18, v60 row_ror:2 row_mask:0xf bank_mask:0xf
	v_mov_b32_dpp v19, v61 row_ror:2 row_mask:0xf bank_mask:0xf
	v_mov_b32_dpp v11, v60 row_ror:1 row_mask:0xf bank_mask:0xf
	v_mov_b32_dpp v14, v61 row_ror:1 row_mask:0xf bank_mask:0xf
	v_cndmask_b32_e64 v19, v39, v19, s[6:7]
	v_cndmask_b32_e64 v18, v37, v18, s[6:7]
	v_cndmask_b32_e64 v15, v14, v38, s[4:5]
	v_cndmask_b32_e64 v14, v11, v36, s[4:5]
	v_pk_mul_f32 v[18:19], v[100:101], v[18:19]
	v_cvt_pk_bf16_f32 v8, v22, v23
	v_pk_fma_f32 v[14:15], v[104:105], v[14:15], v[18:19]
	s_nop 0
	v_pk_fma_f32 v[14:15], v[60:61], v[108:109], v[14:15]
	s_nop 0
	v_mul_f32_e32 v11, 0xbfb8aa3b, v14
	v_exp_f32_e32 v18, v11
	v_mul_f32_e32 v11, 0xbfb8aa3b, v15
	v_exp_f32_e32 v19, v11
	v_cvt_pk_bf16_f32 v11, v16, v17
	v_add_f32_e32 v16, 1.0, v18
	v_rcp_f32_e32 v16, v16
	v_add_f32_e32 v17, 1.0, v19
	v_rcp_f32_e32 v17, v17
	v_mad_i64_i32 v[18:19], s[0:1], v206, s94, v[12:13]
	v_lshl_add_u64 v[18:19], v[18:19], 0, v[112:113]
	global_store_dwordx4 v[18:19], v[8:11], off
	s_nop 1
	v_pk_mul_f32 v[8:9], v[14:15], v[16:17]
	v_mov_b32_dpp v14, v62 row_ror:2 row_mask:0xf bank_mask:0xf
	v_mov_b32_dpp v15, v63 row_ror:2 row_mask:0xf bank_mask:0xf
	v_mov_b32_dpp v10, v62 row_ror:1 row_mask:0xf bank_mask:0xf
	v_mov_b32_dpp v11, v63 row_ror:1 row_mask:0xf bank_mask:0xf
	v_cndmask_b32_e64 v15, v33, v15, s[6:7]
	v_cndmask_b32_e64 v14, v31, v14, s[6:7]
	v_cndmask_b32_e64 v11, v11, v32, s[4:5]
	v_cndmask_b32_e64 v10, v10, v30, s[4:5]
	v_pk_mul_f32 v[14:15], v[102:103], v[14:15]
	v_pk_fma_f32 v[10:11], v[106:107], v[10:11], v[14:15]
	v_pk_fma_f32 v[10:11], v[62:63], v[110:111], v[10:11]
	v_pk_mul_f32 v[4:5], v[4:5], v[8:9]
	v_mul_f32_e32 v14, 0xbfb8aa3b, v10
	v_mul_f32_e32 v15, 0xbfb8aa3b, v11
	v_exp_f32_e32 v14, v14
	v_exp_f32_e32 v15, v15
	v_mov_b32_dpp v16, v56 row_ror:2 row_mask:0xf bank_mask:0xf
	v_mov_b32_dpp v17, v57 row_ror:2 row_mask:0xf bank_mask:0xf
	v_add_f32_e32 v8, 1.0, v14
	v_add_f32_e32 v9, 1.0, v15
	v_cndmask_b32_e64 v17, v41, v17, s[6:7]
	v_mov_b32_dpp v14, v56 row_ror:1 row_mask:0xf bank_mask:0xf
	v_mov_b32_dpp v15, v57 row_ror:1 row_mask:0xf bank_mask:0xf
	v_cndmask_b32_e64 v16, v35, v16, s[6:7]
	v_cndmask_b32_e64 v15, v15, v40, s[4:5]
	v_cndmask_b32_e64 v14, v14, v34, s[4:5]
	v_pk_mul_f32 v[16:17], v[88:89], v[16:17]
	v_rcp_f32_e32 v8, v8
	v_pk_fma_f32 v[14:15], v[92:93], v[14:15], v[16:17]
	v_rcp_f32_e32 v9, v9
	v_pk_fma_f32 v[14:15], v[56:57], v[96:97], v[14:15]
	v_mov_b32_dpp v18, v58 row_ror:2 row_mask:0xf bank_mask:0xf
	v_mul_f32_e32 v16, 0xbfb8aa3b, v14
	v_mul_f32_e32 v17, 0xbfb8aa3b, v15
	v_exp_f32_e32 v16, v16
	v_exp_f32_e32 v17, v17
	v_pk_mul_f32 v[8:9], v[10:11], v[8:9]
	v_mov_b32_dpp v19, v59 row_ror:2 row_mask:0xf bank_mask:0xf
	v_add_f32_e32 v10, 1.0, v16
	v_add_f32_e32 v11, 1.0, v17
	v_cndmask_b32_e64 v19, v45, v19, s[6:7]
	v_mov_b32_dpp v16, v58 row_ror:1 row_mask:0xf bank_mask:0xf
	v_mov_b32_dpp v17, v59 row_ror:1 row_mask:0xf bank_mask:0xf
	v_cndmask_b32_e64 v18, v43, v18, s[6:7]
	v_cndmask_b32_e64 v17, v17, v44, s[4:5]
	v_cndmask_b32_e64 v16, v16, v42, s[4:5]
	v_pk_mul_f32 v[18:19], v[90:91], v[18:19]
	v_rcp_f32_e32 v10, v10
	v_pk_fma_f32 v[16:17], v[94:95], v[16:17], v[18:19]
	v_rcp_f32_e32 v11, v11
	v_pk_fma_f32 v[16:17], v[58:59], v[98:99], v[16:17]
	v_pk_mul_f32 v[6:7], v[6:7], v[8:9]
	v_mul_f32_e32 v18, 0xbfb8aa3b, v16
	v_mul_f32_e32 v19, 0xbfb8aa3b, v17
	v_exp_f32_e32 v18, v18
	v_exp_f32_e32 v19, v19
	v_pk_mul_f32 v[8:9], v[14:15], v[10:11]
	v_add_f32_e32 v18, 1.0, v18
	v_add_f32_e32 v19, 1.0, v19
	v_rcp_f32_e32 v18, v18
	v_rcp_f32_e32 v19, v19
	v_pk_mul_f32 v[8:9], v[0:1], v[8:9]
	v_pk_mul_f32 v[0:1], v[16:17], v[18:19]
	s_nop 0
	v_pk_mul_f32 v[10:11], v[2:3], v[0:1]
	v_cvt_pk_bf16_f32 v0, v4, v5
	v_mad_i64_i32 v[4:5], s[0:1], v202, s94, v[12:13]
	v_cvt_pk_bf16_f32 v1, v6, v7
	v_cvt_pk_bf16_f32 v2, v8, v9
	v_cvt_pk_bf16_f32 v3, v10, v11
	v_lshl_add_u64 v[4:5], v[4:5], 0, v[112:113]
	s_mov_b64 s[0:1], -1
	global_store_dwordx4 v[4:5], v[0:3], off
	s_cbranch_vccnz .LBB0_1149
	s_andn2_b64 vcc, exec, s[36:37]
	s_cbranch_vccnz .LBB0_1148
	s_barrier
	s_branch .LBB0_1148
